# compressed-block phase selection loop unrolled over the four heads: each copy reads its head's Q bank directly (no per-iteration register-bank rotation)
# speedup vs baseline: 1.0143x; 1.0143x over previous
; __device__ __forceinline__ int crow(int r, int hi) { return (r & 3) + 8 * (r >> 2) + 4 * hi; }
; __device__ __forceinline__ void cmp_phase(LAS unsigned char* lds, const bf16_t* __restrict__ P, const bf16_t* __restrict__ Kc, const bf16_t* __restrict__ Vc,
;                                           bf16_t* __restrict__ ocmp, unsigned long long* __restrict__ mask, int G, const int wave0) {
;     ...
;                     CMP_QK(c)
;                     const float m_h = mi[(hh * 32 + r32) * 2], i_h = mi[(hh * 32 + r32) * 2 + 1];
;                     if (16 * (64 * c + 63) + 31 > tw0) {
; #pragma unroll
;                         for (int r = 0; r < 16; ++r) {
;                             const int nc = 64 * c + crow(r, hi);
;                             p0[r] = (16 * nc + 31 <= tq) ? p0[r] : -INFINITY; p1[r] = (16 * (nc + 32) + 31 <= tq) ? p1[r] : -INFINITY;
;                         }
;                     }
.LBB0_780:
	v_add_u32_e32 v90, s74, v92
	v_add_u32_e32 v90, 0x21400, v90
	ds_read_b64 v[90:91], v90
	s_andn2_b64 vcc, exec, s[84:85]
	s_waitcnt lgkmcnt(8)
	v_mfma_f32_32x32x16_bf16 v[16:31], v[32:35], v[146:149], 0
	s_waitcnt lgkmcnt(6)
	v_mfma_f32_32x32x16_bf16 v[0:15], v[40:43], v[146:149], 0
	v_mfma_f32_32x32x16_bf16 v[16:31], v[36:39], v[150:153], v[16:31]
	s_waitcnt lgkmcnt(5)
	v_mfma_f32_32x32x16_bf16 v[0:15], v[44:47], v[150:153], v[0:15]
	s_waitcnt lgkmcnt(4)
	v_mfma_f32_32x32x16_bf16 v[16:31], v[48:51], v[154:157], v[16:31]
	s_waitcnt lgkmcnt(2)
	v_mfma_f32_32x32x16_bf16 v[0:15], v[56:59], v[154:157], v[0:15]
	v_mfma_f32_32x32x16_bf16 v[16:31], v[52:55], v[158:161], v[16:31]
	s_waitcnt lgkmcnt(1)
	v_mfma_f32_32x32x16_bf16 v[0:15], v[60:63], v[158:161], v[0:15]
	s_cbranch_vccnz .Lsu0_779
	s_nop 8
	v_cndmask_b32_e64 v16, v16, v249, s[4:5]
	s_nop 0
	v_cndmask_b32_e64 v0, v0, v249, s[6:7]
	v_cndmask_b32_e64 v17, v17, v249, s[8:9]
	v_cndmask_b32_e64 v1, v1, v249, s[10:11]
	v_cndmask_b32_e64 v18, v18, v249, s[12:13]
	v_cndmask_b32_e64 v2, v2, v249, s[14:15]
	v_cndmask_b32_e64 v19, v19, v249, s[16:17]
	v_cndmask_b32_e64 v3, v3, v249, s[18:19]
	v_cndmask_b32_e64 v20, v20, v249, s[20:21]
	v_cndmask_b32_e64 v4, v4, v249, s[22:23]
	v_cndmask_b32_e64 v21, v21, v249, s[24:25]
	v_cndmask_b32_e64 v5, v5, v249, s[26:27]
	v_cndmask_b32_e64 v22, v22, v249, s[28:29]
	v_cndmask_b32_e64 v6, v6, v249, s[30:31]
	v_cndmask_b32_e64 v23, v23, v249, s[34:35]
	v_cndmask_b32_e64 v7, v7, v249, s[36:37]
	v_cndmask_b32_e64 v24, v24, v249, s[38:39]
	v_cndmask_b32_e64 v8, v8, v249, s[40:41]
	v_cndmask_b32_e64 v25, v25, v249, s[42:43]
	v_cndmask_b32_e64 v9, v9, v249, s[44:45]
	v_cndmask_b32_e64 v26, v26, v249, s[46:47]
	v_cndmask_b32_e64 v10, v10, v249, s[48:49]
	v_cndmask_b32_e64 v27, v27, v249, s[50:51]
	v_cndmask_b32_e64 v11, v11, v249, s[52:53]
	v_cndmask_b32_e64 v28, v28, v249, s[54:55]
	v_cndmask_b32_e64 v12, v12, v249, s[56:57]
	v_cndmask_b32_e64 v29, v29, v249, s[58:59]
	v_cndmask_b32_e64 v13, v13, v249, s[60:61]
	v_cndmask_b32_e64 v30, v30, v249, s[62:63]
	v_cndmask_b32_e64 v14, v14, v249, s[64:65]
	v_cndmask_b32_e64 v31, v31, v249, s[66:67]
	v_cndmask_b32_e64 v15, v15, v249, s[68:69]
; __device__ __forceinline__ int crow(int r, int hi) { return (r & 3) + 8 * (r >> 2) + 4 * hi; }
; __device__ __forceinline__ void cmp_phase(LAS unsigned char* lds, const bf16_t* __restrict__ P, const bf16_t* __restrict__ Kc, const bf16_t* __restrict__ Vc,
;                                           bf16_t* __restrict__ ocmp, unsigned long long* __restrict__ mask, int G, const int wave0) {
;     ...
;                     CMP_QK(c)
;                     const float m_h = mi[(hh * 32 + r32) * 2], i_h = mi[(hh * 32 + r32) * 2 + 1];
;                     if (16 * (64 * c + 63) + 31 > tw0) {
; #pragma unroll
;                         for (int r = 0; r < 16; ++r) {
;                             const int nc = 64 * c + crow(r, hi);
;                             p0[r] = (16 * nc + 31 <= tq) ? p0[r] : -INFINITY; p1[r] = (16 * (nc + 32) + 31 <= tq) ? p1[r] : -INFINITY;
;                         }
;                     }
; #pragma unroll
;                     for (int r = 0; r < 16; ++r) { p0[r] = __builtin_amdgcn_exp2f(p0[r] - m_h) * i_h; p1[r] = __builtin_amdgcn_exp2f(p1[r] - m_h) * i_h; }
; #pragma unroll
;                     for (int k = 0; k < 4; ++k) {
;                         A8[k] += p0[4 * k] + 2.0f * (p0[4 * k + 1] + p0[4 * k + 2] + p0[4 * k + 3]); B8[k] += p0[4 * k];
;                         A8[4 + k] += p1[4 * k] + 2.0f * (p1[4 * k + 1] + p1[4 * k + 2] + p1[4 * k + 3]); B8[4 + k] += p1[4 * k];
;                     }
.Lsu0_779:
	s_waitcnt lgkmcnt(0)
	s_nop 9
	v_sub_f32_e32 v1, v1, v90
	v_exp_f32_e32 v96, v1
	v_sub_f32_e32 v1, v18, v90
	v_exp_f32_e32 v18, v1
	v_sub_f32_e32 v1, v2, v90
	v_exp_f32_e32 v2, v1
	v_sub_f32_e32 v1, v19, v90
	v_exp_f32_e32 v100, v1
	v_sub_f32_e32 v1, v3, v90
	v_sub_f32_e32 v3, v21, v90
	v_exp_f32_e32 v95, v3
	v_sub_f32_e32 v3, v5, v90
	v_exp_f32_e32 v97, v3
	v_sub_f32_e32 v3, v22, v90
	v_sub_f32_e32 v5, v8, v90
	v_exp_f32_e32 v19, v3
	v_sub_f32_e32 v3, v6, v90
	v_exp_f32_e32 v6, v5
	v_sub_f32_e32 v5, v25, v90
	v_exp_f32_e32 v8, v5
	v_sub_f32_e32 v5, v9, v90
	v_sub_f32_e32 v17, v17, v90
	v_exp_f32_e32 v102, v1
	v_sub_f32_e32 v1, v20, v90
	v_exp_f32_e32 v20, v5
	v_sub_f32_e32 v5, v26, v90
	v_exp_f32_e32 v94, v17
	v_exp_f32_e32 v17, v1
	v_sub_f32_e32 v1, v4, v90
	v_exp_f32_e32 v3, v3
	v_sub_f32_e32 v4, v23, v90
	v_exp_f32_e32 v22, v5
	v_sub_f32_e32 v5, v10, v90
	v_exp_f32_e32 v101, v4
	v_sub_f32_e32 v4, v7, v90
	v_exp_f32_e32 v10, v5
	v_sub_f32_e32 v5, v27, v90
	v_exp_f32_e32 v103, v4
	v_sub_f32_e32 v4, v24, v90
	v_exp_f32_e32 v24, v5
	v_sub_f32_e32 v5, v11, v90
	v_sub_f32_e32 v11, v13, v90
	v_sub_f32_e32 v0, v0, v90
	v_exp_f32_e32 v21, v11
	v_sub_f32_e32 v11, v30, v90
	v_exp_f32_e32 v0, v0
	v_exp_f32_e32 v1, v1
	v_sub_f32_e32 v9, v29, v90
	v_exp_f32_e32 v23, v11
	v_pk_mul_f32 v[2:3], v[90:91], v[2:3] op_sel:[1,0]
	v_sub_f32_e32 v7, v12, v90
	v_exp_f32_e32 v9, v9
	v_sub_f32_e32 v12, v31, v90
	v_pk_fma_f32 v[2:3], v[90:91], v[96:97], v[2:3] op_sel:[1,0,0]
	v_exp_f32_e32 v25, v12
	v_pk_fma_f32 v[2:3], v[90:91], v[102:103], v[2:3] op_sel:[1,0,0]
	v_exp_f32_e32 v26, v5
	v_sub_f32_e32 v5, v28, v90
	v_pk_add_f32 v[2:3], v[2:3], v[2:3]
	v_exp_f32_e32 v4, v4
	v_exp_f32_e32 v5, v5
	v_sub_f32_e32 v11, v14, v90
	v_pk_fma_f32 v[2:3], v[90:91], v[0:1], v[2:3] op_sel:[1,0,0]
	v_pk_fma_f32 v[70:71], v[90:91], v[0:1], v[70:71] op_sel:[1,0,0]
	v_pk_mul_f32 v[0:1], v[90:91], v[22:23] op_sel:[1,0]
	v_exp_f32_e32 v11, v11
	v_pk_fma_f32 v[0:1], v[90:91], v[8:9], v[0:1] op_sel:[1,0,0]
	v_sub_f32_e32 v12, v15, v90
	v_pk_fma_f32 v[0:1], v[90:91], v[24:25], v[0:1] op_sel:[1,0,0]
	v_exp_f32_e32 v27, v12
	v_pk_add_f32 v[0:1], v[0:1], v[0:1]
	v_sub_f32_e32 v16, v16, v90
	v_pk_fma_f32 v[0:1], v[90:91], v[4:5], v[0:1] op_sel:[1,0,0]
	v_exp_f32_e32 v16, v16
	v_exp_f32_e32 v7, v7
	v_pk_mul_f32 v[12:13], v[90:91], v[18:19] op_sel:[1,0]
	v_pk_add_f32 v[84:85], v[84:85], v[0:1]
	v_pk_mul_f32 v[0:1], v[90:91], v[10:11] op_sel:[1,0]
	v_pk_fma_f32 v[12:13], v[90:91], v[94:95], v[12:13] op_sel:[1,0,0]
	v_pk_fma_f32 v[0:1], v[90:91], v[20:21], v[0:1] op_sel:[1,0,0]
	v_pk_fma_f32 v[12:13], v[90:91], v[100:101], v[12:13] op_sel:[1,0,0]
	v_pk_fma_f32 v[0:1], v[90:91], v[26:27], v[0:1] op_sel:[1,0,0]
	v_pk_add_f32 v[12:13], v[12:13], v[12:13]
	v_pk_add_f32 v[0:1], v[0:1], v[0:1]
	v_pk_fma_f32 v[12:13], v[90:91], v[16:17], v[12:13] op_sel:[1,0,0]
	v_pk_fma_f32 v[0:1], v[90:91], v[6:7], v[0:1] op_sel:[1,0,0]
	s_addk_i32 s74, 0x100
	v_pk_add_f32 v[86:87], v[86:87], v[12:13]
	v_pk_fma_f32 v[74:75], v[90:91], v[16:17], v[74:75] op_sel:[1,0,0]
	v_pk_add_f32 v[78:79], v[78:79], v[2:3]
	v_pk_fma_f32 v[72:73], v[90:91], v[4:5], v[72:73] op_sel:[1,0,0]
	v_pk_add_f32 v[76:77], v[76:77], v[0:1]
	v_pk_fma_f32 v[68:69], v[90:91], v[6:7], v[68:69] op_sel:[1,0,0]
	v_lshl_add_u64 v[88:89], v[88:89], 0, s[78:79]
.Lsu1_780:
	v_add_u32_e32 v90, s74, v92
	v_add_u32_e32 v90, 0x21400, v90
	ds_read_b64 v[90:91], v90
	s_andn2_b64 vcc, exec, s[84:85]
	s_waitcnt lgkmcnt(8)
	v_mfma_f32_32x32x16_bf16 v[16:31], v[32:35], v[200:203], 0
	s_waitcnt lgkmcnt(6)
	v_mfma_f32_32x32x16_bf16 v[0:15], v[40:43], v[200:203], 0
	v_mfma_f32_32x32x16_bf16 v[16:31], v[36:39], v[204:207], v[16:31]
	s_waitcnt lgkmcnt(5)
	v_mfma_f32_32x32x16_bf16 v[0:15], v[44:47], v[204:207], v[0:15]
	s_waitcnt lgkmcnt(4)
	v_mfma_f32_32x32x16_bf16 v[16:31], v[48:51], v[208:211], v[16:31]
	s_waitcnt lgkmcnt(2)
	v_mfma_f32_32x32x16_bf16 v[0:15], v[56:59], v[208:211], v[0:15]
	v_mfma_f32_32x32x16_bf16 v[16:31], v[52:55], v[216:219], v[16:31]
	s_waitcnt lgkmcnt(1)
	v_mfma_f32_32x32x16_bf16 v[0:15], v[60:63], v[216:219], v[0:15]
	s_cbranch_vccnz .Lsu1_779
	s_nop 8
	v_cndmask_b32_e64 v16, v16, v249, s[4:5]
	s_nop 0
	v_cndmask_b32_e64 v0, v0, v249, s[6:7]
	v_cndmask_b32_e64 v17, v17, v249, s[8:9]
	v_cndmask_b32_e64 v1, v1, v249, s[10:11]
	v_cndmask_b32_e64 v18, v18, v249, s[12:13]
	v_cndmask_b32_e64 v2, v2, v249, s[14:15]
	v_cndmask_b32_e64 v19, v19, v249, s[16:17]
	v_cndmask_b32_e64 v3, v3, v249, s[18:19]
	v_cndmask_b32_e64 v20, v20, v249, s[20:21]
	v_cndmask_b32_e64 v4, v4, v249, s[22:23]
	v_cndmask_b32_e64 v21, v21, v249, s[24:25]
	v_cndmask_b32_e64 v5, v5, v249, s[26:27]
	v_cndmask_b32_e64 v22, v22, v249, s[28:29]
	v_cndmask_b32_e64 v6, v6, v249, s[30:31]
	v_cndmask_b32_e64 v23, v23, v249, s[34:35]
	v_cndmask_b32_e64 v7, v7, v249, s[36:37]
	v_cndmask_b32_e64 v24, v24, v249, s[38:39]
	v_cndmask_b32_e64 v8, v8, v249, s[40:41]
	v_cndmask_b32_e64 v25, v25, v249, s[42:43]
	v_cndmask_b32_e64 v9, v9, v249, s[44:45]
	v_cndmask_b32_e64 v26, v26, v249, s[46:47]
	v_cndmask_b32_e64 v10, v10, v249, s[48:49]
	v_cndmask_b32_e64 v27, v27, v249, s[50:51]
	v_cndmask_b32_e64 v11, v11, v249, s[52:53]
	v_cndmask_b32_e64 v28, v28, v249, s[54:55]
	v_cndmask_b32_e64 v12, v12, v249, s[56:57]
	v_cndmask_b32_e64 v29, v29, v249, s[58:59]
	v_cndmask_b32_e64 v13, v13, v249, s[60:61]
	v_cndmask_b32_e64 v30, v30, v249, s[62:63]
	v_cndmask_b32_e64 v14, v14, v249, s[64:65]
	v_cndmask_b32_e64 v31, v31, v249, s[66:67]
	v_cndmask_b32_e64 v15, v15, v249, s[68:69]

; __device__ __forceinline__ int crow(int r, int hi) { return (r & 3) + 8 * (r >> 2) + 4 * hi; }
; __device__ __forceinline__ void cmp_phase(LAS unsigned char* lds, const bf16_t* __restrict__ P, const bf16_t* __restrict__ Kc, const bf16_t* __restrict__ Vc,
;                                           bf16_t* __restrict__ ocmp, unsigned long long* __restrict__ mask, int G, const int wave0) {
;     ...
;                     CMP_QK(c)
;                     const float m_h = mi[(hh * 32 + r32) * 2], i_h = mi[(hh * 32 + r32) * 2 + 1];
;                     if (16 * (64 * c + 63) + 31 > tw0) {
; #pragma unroll
;                         for (int r = 0; r < 16; ++r) {
;                             const int nc = 64 * c + crow(r, hi);
;                             p0[r] = (16 * nc + 31 <= tq) ? p0[r] : -INFINITY; p1[r] = (16 * (nc + 32) + 31 <= tq) ? p1[r] : -INFINITY;
;                         }
;                     }
.Lsu2_780:
	v_add_u32_e32 v90, s74, v92
	v_add_u32_e32 v90, 0x21400, v90
	ds_read_b64 v[90:91], v90
	s_andn2_b64 vcc, exec, s[84:85]
	s_waitcnt lgkmcnt(8)
	v_mfma_f32_32x32x16_bf16 v[16:31], v[32:35], v[220:223], 0
	s_waitcnt lgkmcnt(6)
	v_mfma_f32_32x32x16_bf16 v[0:15], v[40:43], v[220:223], 0
	v_mfma_f32_32x32x16_bf16 v[16:31], v[36:39], v[224:227], v[16:31]
	s_waitcnt lgkmcnt(5)
	v_mfma_f32_32x32x16_bf16 v[0:15], v[44:47], v[224:227], v[0:15]
	s_waitcnt lgkmcnt(4)
	v_mfma_f32_32x32x16_bf16 v[16:31], v[48:51], v[228:231], v[16:31]
	s_waitcnt lgkmcnt(2)
	v_mfma_f32_32x32x16_bf16 v[0:15], v[56:59], v[228:231], v[0:15]
	v_mfma_f32_32x32x16_bf16 v[16:31], v[52:55], v[232:235], v[16:31]
	s_waitcnt lgkmcnt(1)
	v_mfma_f32_32x32x16_bf16 v[0:15], v[60:63], v[232:235], v[0:15]
	s_cbranch_vccnz .Lsu2_779
	s_nop 8
	v_cndmask_b32_e64 v16, v16, v249, s[4:5]
	s_nop 0
	v_cndmask_b32_e64 v0, v0, v249, s[6:7]
	v_cndmask_b32_e64 v17, v17, v249, s[8:9]
	v_cndmask_b32_e64 v1, v1, v249, s[10:11]
	v_cndmask_b32_e64 v18, v18, v249, s[12:13]
	v_cndmask_b32_e64 v2, v2, v249, s[14:15]
	v_cndmask_b32_e64 v19, v19, v249, s[16:17]
	v_cndmask_b32_e64 v3, v3, v249, s[18:19]
	v_cndmask_b32_e64 v20, v20, v249, s[20:21]
	v_cndmask_b32_e64 v4, v4, v249, s[22:23]
	v_cndmask_b32_e64 v21, v21, v249, s[24:25]
	v_cndmask_b32_e64 v5, v5, v249, s[26:27]
	v_cndmask_b32_e64 v22, v22, v249, s[28:29]
	v_cndmask_b32_e64 v6, v6, v249, s[30:31]
	v_cndmask_b32_e64 v23, v23, v249, s[34:35]
	v_cndmask_b32_e64 v7, v7, v249, s[36:37]
	v_cndmask_b32_e64 v24, v24, v249, s[38:39]
	v_cndmask_b32_e64 v8, v8, v249, s[40:41]
	v_cndmask_b32_e64 v25, v25, v249, s[42:43]
	v_cndmask_b32_e64 v9, v9, v249, s[44:45]
	v_cndmask_b32_e64 v26, v26, v249, s[46:47]
	v_cndmask_b32_e64 v10, v10, v249, s[48:49]
	v_cndmask_b32_e64 v27, v27, v249, s[50:51]
	v_cndmask_b32_e64 v11, v11, v249, s[52:53]
	v_cndmask_b32_e64 v28, v28, v249, s[54:55]
	v_cndmask_b32_e64 v12, v12, v249, s[56:57]
	v_cndmask_b32_e64 v29, v29, v249, s[58:59]
	v_cndmask_b32_e64 v13, v13, v249, s[60:61]
	v_cndmask_b32_e64 v30, v30, v249, s[62:63]
	v_cndmask_b32_e64 v14, v14, v249, s[64:65]
	v_cndmask_b32_e64 v31, v31, v249, s[66:67]
	v_cndmask_b32_e64 v15, v15, v249, s[68:69]

; __device__ __forceinline__ int crow(int r, int hi) { return (r & 3) + 8 * (r >> 2) + 4 * hi; }
; __device__ __forceinline__ void cmp_phase(LAS unsigned char* lds, const bf16_t* __restrict__ P, const bf16_t* __restrict__ Kc, const bf16_t* __restrict__ Vc,
;                                           bf16_t* __restrict__ ocmp, unsigned long long* __restrict__ mask, int G, const int wave0) {
;     ...
;                     CMP_QK(c)
;                     const float m_h = mi[(hh * 32 + r32) * 2], i_h = mi[(hh * 32 + r32) * 2 + 1];
;                     if (16 * (64 * c + 63) + 31 > tw0) {
; #pragma unroll
;                         for (int r = 0; r < 16; ++r) {
;                             const int nc = 64 * c + crow(r, hi);
;                             p0[r] = (16 * nc + 31 <= tq) ? p0[r] : -INFINITY; p1[r] = (16 * (nc + 32) + 31 <= tq) ? p1[r] : -INFINITY;
;                         }
;                     }
; #pragma unroll
;                     for (int r = 0; r < 16; ++r) { p0[r] = __builtin_amdgcn_exp2f(p0[r] - m_h) * i_h; p1[r] = __builtin_amdgcn_exp2f(p1[r] - m_h) * i_h; }
; #pragma unroll
;                     for (int k = 0; k < 4; ++k) {
;                         A8[k] += p0[4 * k] + 2.0f * (p0[4 * k + 1] + p0[4 * k + 2] + p0[4 * k + 3]); B8[k] += p0[4 * k];
;                         A8[4 + k] += p1[4 * k] + 2.0f * (p1[4 * k + 1] + p1[4 * k + 2] + p1[4 * k + 3]); B8[4 + k] += p1[4 * k];
;                     }
.Lsu3_780:
	v_add_u32_e32 v90, s74, v92
	v_add_u32_e32 v90, 0x21400, v90
	ds_read_b64 v[90:91], v90
	s_andn2_b64 vcc, exec, s[84:85]
	s_waitcnt lgkmcnt(8)
	v_mfma_f32_32x32x16_bf16 v[16:31], v[32:35], v[130:133], 0
	s_waitcnt lgkmcnt(6)
	v_mfma_f32_32x32x16_bf16 v[0:15], v[40:43], v[130:133], 0
	v_mfma_f32_32x32x16_bf16 v[16:31], v[36:39], v[134:137], v[16:31]
	s_waitcnt lgkmcnt(5)
	v_mfma_f32_32x32x16_bf16 v[0:15], v[44:47], v[134:137], v[0:15]
	s_waitcnt lgkmcnt(4)
	v_mfma_f32_32x32x16_bf16 v[16:31], v[48:51], v[138:141], v[16:31]
	s_waitcnt lgkmcnt(2)
	v_mfma_f32_32x32x16_bf16 v[0:15], v[56:59], v[138:141], v[0:15]
	v_mfma_f32_32x32x16_bf16 v[16:31], v[52:55], v[142:145], v[16:31]
	s_waitcnt lgkmcnt(1)
	v_mfma_f32_32x32x16_bf16 v[0:15], v[60:63], v[142:145], v[0:15]
	s_cbranch_vccnz .Lsu3_779
	s_nop 8
	v_cndmask_b32_e64 v16, v16, v249, s[4:5]
	s_nop 0
	v_cndmask_b32_e64 v0, v0, v249, s[6:7]
	v_cndmask_b32_e64 v17, v17, v249, s[8:9]
	v_cndmask_b32_e64 v1, v1, v249, s[10:11]
	v_cndmask_b32_e64 v18, v18, v249, s[12:13]
	v_cndmask_b32_e64 v2, v2, v249, s[14:15]
	v_cndmask_b32_e64 v19, v19, v249, s[16:17]
	v_cndmask_b32_e64 v3, v3, v249, s[18:19]
	v_cndmask_b32_e64 v20, v20, v249, s[20:21]
	v_cndmask_b32_e64 v4, v4, v249, s[22:23]
	v_cndmask_b32_e64 v21, v21, v249, s[24:25]
	v_cndmask_b32_e64 v5, v5, v249, s[26:27]
	v_cndmask_b32_e64 v22, v22, v249, s[28:29]
	v_cndmask_b32_e64 v6, v6, v249, s[30:31]
	v_cndmask_b32_e64 v23, v23, v249, s[34:35]
	v_cndmask_b32_e64 v7, v7, v249, s[36:37]
	v_cndmask_b32_e64 v24, v24, v249, s[38:39]
	v_cndmask_b32_e64 v8, v8, v249, s[40:41]
	v_cndmask_b32_e64 v25, v25, v249, s[42:43]
	v_cndmask_b32_e64 v9, v9, v249, s[44:45]
	v_cndmask_b32_e64 v26, v26, v249, s[46:47]
	v_cndmask_b32_e64 v10, v10, v249, s[48:49]
	v_cndmask_b32_e64 v27, v27, v249, s[50:51]
	v_cndmask_b32_e64 v11, v11, v249, s[52:53]
	v_cndmask_b32_e64 v28, v28, v249, s[54:55]
	v_cndmask_b32_e64 v12, v12, v249, s[56:57]
	v_cndmask_b32_e64 v29, v29, v249, s[58:59]
	v_cndmask_b32_e64 v13, v13, v249, s[60:61]
	v_cndmask_b32_e64 v30, v30, v249, s[62:63]
	v_cndmask_b32_e64 v14, v14, v249, s[64:65]
	v_cndmask_b32_e64 v31, v31, v249, s[66:67]
	v_cndmask_b32_e64 v15, v15, v249, s[68:69]
.Lsu3_779:
	s_waitcnt lgkmcnt(0)
	s_nop 9
	v_sub_f32_e32 v1, v1, v90
	v_exp_f32_e32 v96, v1
	v_sub_f32_e32 v1, v18, v90
	v_exp_f32_e32 v18, v1
	v_sub_f32_e32 v1, v2, v90
	v_exp_f32_e32 v2, v1
	v_sub_f32_e32 v1, v19, v90
	v_exp_f32_e32 v100, v1
	v_sub_f32_e32 v1, v3, v90
	v_sub_f32_e32 v3, v21, v90
	v_exp_f32_e32 v95, v3
	v_sub_f32_e32 v3, v5, v90
	v_exp_f32_e32 v97, v3
	v_sub_f32_e32 v3, v22, v90
	v_sub_f32_e32 v5, v8, v90
	v_exp_f32_e32 v19, v3
	v_sub_f32_e32 v3, v6, v90
	v_exp_f32_e32 v6, v5
	v_sub_f32_e32 v5, v25, v90
	v_exp_f32_e32 v8, v5
	v_sub_f32_e32 v5, v9, v90
	v_sub_f32_e32 v17, v17, v90
	v_exp_f32_e32 v102, v1
	v_sub_f32_e32 v1, v20, v90
	v_exp_f32_e32 v20, v5
	v_sub_f32_e32 v5, v26, v90
	v_exp_f32_e32 v94, v17
	v_exp_f32_e32 v17, v1
	v_sub_f32_e32 v1, v4, v90
	v_exp_f32_e32 v3, v3
	v_sub_f32_e32 v4, v23, v90
	v_exp_f32_e32 v22, v5
	v_sub_f32_e32 v5, v10, v90
	v_exp_f32_e32 v101, v4
	v_sub_f32_e32 v4, v7, v90
	v_exp_f32_e32 v10, v5
	v_sub_f32_e32 v5, v27, v90
	v_exp_f32_e32 v103, v4
	v_sub_f32_e32 v4, v24, v90
	v_exp_f32_e32 v24, v5
	v_sub_f32_e32 v5, v11, v90
	v_sub_f32_e32 v11, v13, v90
	v_sub_f32_e32 v0, v0, v90
	v_exp_f32_e32 v21, v11
	v_sub_f32_e32 v11, v30, v90
	v_exp_f32_e32 v0, v0
	v_exp_f32_e32 v1, v1
	v_sub_f32_e32 v9, v29, v90
	v_exp_f32_e32 v23, v11
	v_pk_mul_f32 v[2:3], v[90:91], v[2:3] op_sel:[1,0]
	v_sub_f32_e32 v7, v12, v90
	v_exp_f32_e32 v9, v9
	v_sub_f32_e32 v12, v31, v90
	v_pk_fma_f32 v[2:3], v[90:91], v[96:97], v[2:3] op_sel:[1,0,0]
	v_exp_f32_e32 v25, v12
	v_pk_fma_f32 v[2:3], v[90:91], v[102:103], v[2:3] op_sel:[1,0,0]
	v_exp_f32_e32 v26, v5
	v_sub_f32_e32 v5, v28, v90
	v_pk_add_f32 v[2:3], v[2:3], v[2:3]
	v_exp_f32_e32 v4, v4
	v_exp_f32_e32 v5, v5
	v_sub_f32_e32 v11, v14, v90
	v_pk_fma_f32 v[2:3], v[90:91], v[0:1], v[2:3] op_sel:[1,0,0]
	v_pk_fma_f32 v[70:71], v[90:91], v[0:1], v[70:71] op_sel:[1,0,0]
	v_pk_mul_f32 v[0:1], v[90:91], v[22:23] op_sel:[1,0]
	v_exp_f32_e32 v11, v11
	v_pk_fma_f32 v[0:1], v[90:91], v[8:9], v[0:1] op_sel:[1,0,0]
	v_sub_f32_e32 v12, v15, v90
	v_pk_fma_f32 v[0:1], v[90:91], v[24:25], v[0:1] op_sel:[1,0,0]
	v_exp_f32_e32 v27, v12
	v_pk_add_f32 v[0:1], v[0:1], v[0:1]
	v_sub_f32_e32 v16, v16, v90
	v_pk_fma_f32 v[0:1], v[90:91], v[4:5], v[0:1] op_sel:[1,0,0]
	v_exp_f32_e32 v16, v16
	v_exp_f32_e32 v7, v7
	v_pk_mul_f32 v[12:13], v[90:91], v[18:19] op_sel:[1,0]
	v_pk_add_f32 v[84:85], v[84:85], v[0:1]
	v_pk_mul_f32 v[0:1], v[90:91], v[10:11] op_sel:[1,0]
	v_pk_fma_f32 v[12:13], v[90:91], v[94:95], v[12:13] op_sel:[1,0,0]
	v_pk_fma_f32 v[0:1], v[90:91], v[20:21], v[0:1] op_sel:[1,0,0]
	v_pk_fma_f32 v[12:13], v[90:91], v[100:101], v[12:13] op_sel:[1,0,0]
	v_pk_fma_f32 v[0:1], v[90:91], v[26:27], v[0:1] op_sel:[1,0,0]
	v_pk_add_f32 v[12:13], v[12:13], v[12:13]
	v_pk_add_f32 v[0:1], v[0:1], v[0:1]
	v_pk_fma_f32 v[12:13], v[90:91], v[16:17], v[12:13] op_sel:[1,0,0]
	v_pk_fma_f32 v[0:1], v[90:91], v[6:7], v[0:1] op_sel:[1,0,0]
	s_addk_i32 s74, 0x100
	v_pk_add_f32 v[86:87], v[86:87], v[12:13]
	v_pk_fma_f32 v[74:75], v[90:91], v[16:17], v[74:75] op_sel:[1,0,0]
	v_pk_add_f32 v[78:79], v[78:79], v[2:3]
	v_pk_fma_f32 v[72:73], v[90:91], v[4:5], v[72:73] op_sel:[1,0,0]
	v_pk_add_f32 v[76:77], v[76:77], v[0:1]
	v_pk_fma_f32 v[68:69], v[90:91], v[6:7], v[68:69] op_sel:[1,0,0]
	v_lshl_add_u64 v[88:89], v[88:89], 0, s[78:79]
	s_branch .LBB0_775
